# attention-group merge: loads of all 4 tasks per thread issued up front (4 register sets), counted vmcnt waits; original loop kept as fallback
# speedup vs baseline: 1.0028x; 1.0003x over previous
.LBB0_609:
	s_cmp_lt_i32 s86, 4
	s_cselect_b64 s[2:3], -1, 0
	s_and_b64 s[4:5], s[2:3], s[0:1]
	s_andn2_b64 vcc, exec, s[4:5]
	s_cbranch_vccnz .LBB0_619
	v_lshl_add_u32 v1, s94, 9, v165
	s_mov_b32 s0, 0x80000
	s_lshl_b32 s2, s88, 9
	v_cmp_gt_i32_e32 vcc, s0, v1
	s_and_saveexec_b64 s[0:1], vcc
	s_cbranch_execz .LBB0_613
	s_add_u32 s6, s82, 0x2800000
	s_addc_u32 s7, s83, 0
	s_add_u32 s8, s82, 0x3000000
	s_waitcnt vmcnt(0)
	v_lshlrev_b32_e32 v2, 3, v165
	s_addc_u32 s9, s83, 0
	v_lshl_add_u32 v6, s94, 12, v2
	s_lshl_b32 s3, s88, 12
	s_mov_b64 s[10:11], 0
	v_mov_b32_e32 v3, 0
	s_movk_i32 s12, 0xc00
	v_mov_b64_e32 v[4:5], s[62:63]
	s_mov_b32 s13, 0x7ffff
	v_mov_b32_e32 v7, v1
	s_cmp_lg_u32 s88, 0x100
	s_cbranch_scc1 .LBB0_612
	v_mov_b32_e32 v151, 0
	v_mov_b32_e32 v153, 0
	v_mov_b32_e32 v155, 0
	v_ashrrev_i32_e32 v8, 6, v7
	v_bfe_u32 v14, v7, 4, 2
	v_ashrrev_i32_e32 v9, 31, v8
	v_add_u32_e32 v7, s2, v7
	v_lshlrev_b32_e32 v2, 2, v14
	v_lshl_add_u64 v[12:13], v[8:9], 4, s[50:51]
	v_and_b32_e32 v15, 0x78, v6
	v_lshlrev_b32_e32 v18, 7, v14
	s_waitcnt lgkmcnt(0)
	v_mad_i64_i32 v[10:11], s[14:15], v8, s12, v[4:5]
	v_lshlrev_b64 v[8:9], 9, v[8:9]
	v_lshl_add_u64 v[16:17], v[12:13], 0, v[2:3]
	v_or3_b32 v8, v8, v18, v15
	v_add_co_u32_e32 v18, vcc, 0x20000, v16
	v_lshlrev_b32_e32 v2, 8, v14
	s_nop 0
	v_addc_co_u32_e32 v19, vcc, 0, v17, vcc
	global_load_dword v30, v[16:17], off
	v_lshlrev_b64 v[8:9], 1, v[8:9]
	v_add_co_u32_e32 v16, vcc, 0x40000, v16
	v_lshl_add_u64 v[10:11], v[10:11], 0, v[2:3]
	v_lshlrev_b32_e32 v2, 1, v15
	v_lshl_add_u64 v[12:13], s[48:49], 0, v[8:9]
	v_lshl_add_u64 v[14:15], s[6:7], 0, v[8:9]
	v_addc_co_u32_e32 v17, vcc, 0, v17, vcc
	v_lshl_add_u64 v[20:21], s[8:9], 0, v[8:9]
	v_lshl_add_u64 v[22:23], v[10:11], 0, v[2:3]
	global_load_dwordx4 v[8:11], v[14:15], off
	s_nop 0
	global_load_dwordx4 v[12:15], v[12:13], off
	s_nop 0
	global_load_dword v2, v[18:19], off
	global_load_dword v31, v[16:17], off
	s_nop 0
	global_load_dwordx4 v[16:19], v[20:21], off
	v_add_u32_e32 v6, s3, v6
	v_ashrrev_i32_e32 v44, 6, v7
	v_bfe_u32 v50, v7, 4, 2
	v_ashrrev_i32_e32 v45, 31, v44
	v_add_u32_e32 v7, s2, v7
	v_lshlrev_b32_e32 v150, 2, v50
	v_lshl_add_u64 v[48:49], v[44:45], 4, s[50:51]
	v_and_b32_e32 v51, 0x78, v6
	v_lshlrev_b32_e32 v54, 7, v50
	s_waitcnt lgkmcnt(0)
	v_mad_i64_i32 v[46:47], s[14:15], v44, s12, v[4:5]
	v_lshlrev_b64 v[44:45], 9, v[44:45]
	v_lshl_add_u64 v[52:53], v[48:49], 0, v[150:151]
	v_or3_b32 v44, v44, v54, v51
	v_add_co_u32_e32 v54, vcc, 0x20000, v52
	v_lshlrev_b32_e32 v150, 8, v50
	s_nop 0
	v_addc_co_u32_e32 v55, vcc, 0, v53, vcc
	global_load_dword v66, v[52:53], off
	v_lshlrev_b64 v[44:45], 1, v[44:45]
	v_add_co_u32_e32 v52, vcc, 0x40000, v52
	v_lshl_add_u64 v[46:47], v[46:47], 0, v[150:151]
	v_lshlrev_b32_e32 v150, 1, v51
	v_lshl_add_u64 v[48:49], s[48:49], 0, v[44:45]
	v_lshl_add_u64 v[50:51], s[6:7], 0, v[44:45]
	v_addc_co_u32_e32 v53, vcc, 0, v53, vcc
	v_lshl_add_u64 v[56:57], s[8:9], 0, v[44:45]
	v_lshl_add_u64 v[58:59], v[46:47], 0, v[150:151]
	global_load_dwordx4 v[44:47], v[50:51], off
	s_nop 0
	global_load_dwordx4 v[48:51], v[48:49], off
	s_nop 0
	global_load_dword v150, v[54:55], off
	global_load_dword v67, v[52:53], off
	s_nop 0
	global_load_dwordx4 v[52:55], v[56:57], off
	v_add_u32_e32 v6, s3, v6
	v_ashrrev_i32_e32 v80, 6, v7
	v_bfe_u32 v86, v7, 4, 2
	v_ashrrev_i32_e32 v81, 31, v80
	v_add_u32_e32 v7, s2, v7
	v_lshlrev_b32_e32 v152, 2, v86
	v_lshl_add_u64 v[84:85], v[80:81], 4, s[50:51]
	v_and_b32_e32 v87, 0x78, v6
	v_lshlrev_b32_e32 v90, 7, v86
	s_waitcnt lgkmcnt(0)
	v_mad_i64_i32 v[82:83], s[14:15], v80, s12, v[4:5]
	v_lshlrev_b64 v[80:81], 9, v[80:81]
	v_lshl_add_u64 v[88:89], v[84:85], 0, v[152:153]
	v_or3_b32 v80, v80, v90, v87
	v_add_co_u32_e32 v90, vcc, 0x20000, v88
	v_lshlrev_b32_e32 v152, 8, v86
	s_nop 0
	v_addc_co_u32_e32 v91, vcc, 0, v89, vcc
	global_load_dword v102, v[88:89], off
	v_lshlrev_b64 v[80:81], 1, v[80:81]
	v_add_co_u32_e32 v88, vcc, 0x40000, v88
	v_lshl_add_u64 v[82:83], v[82:83], 0, v[152:153]
	v_lshlrev_b32_e32 v152, 1, v87
	v_lshl_add_u64 v[84:85], s[48:49], 0, v[80:81]
	v_lshl_add_u64 v[86:87], s[6:7], 0, v[80:81]
	v_addc_co_u32_e32 v89, vcc, 0, v89, vcc
	v_lshl_add_u64 v[92:93], s[8:9], 0, v[80:81]
	v_lshl_add_u64 v[94:95], v[82:83], 0, v[152:153]
	global_load_dwordx4 v[80:83], v[86:87], off
	s_nop 0
	global_load_dwordx4 v[84:87], v[84:85], off
	s_nop 0
	global_load_dword v152, v[90:91], off
	global_load_dword v103, v[88:89], off
	s_nop 0
	global_load_dwordx4 v[88:91], v[92:93], off
	v_add_u32_e32 v6, s3, v6
	v_ashrrev_i32_e32 v116, 6, v7
	v_bfe_u32 v122, v7, 4, 2
	v_ashrrev_i32_e32 v117, 31, v116
	v_add_u32_e32 v7, s2, v7
	v_lshlrev_b32_e32 v154, 2, v122
	v_lshl_add_u64 v[120:121], v[116:117], 4, s[50:51]
	v_and_b32_e32 v123, 0x78, v6
	v_lshlrev_b32_e32 v126, 7, v122
	s_waitcnt lgkmcnt(0)
	v_mad_i64_i32 v[118:119], s[14:15], v116, s12, v[4:5]
	v_lshlrev_b64 v[116:117], 9, v[116:117]
	v_lshl_add_u64 v[124:125], v[120:121], 0, v[154:155]
	v_or3_b32 v116, v116, v126, v123
	v_add_co_u32_e32 v126, vcc, 0x20000, v124
	v_lshlrev_b32_e32 v154, 8, v122
	s_nop 0
	v_addc_co_u32_e32 v127, vcc, 0, v125, vcc
	global_load_dword v138, v[124:125], off
	v_lshlrev_b64 v[116:117], 1, v[116:117]
	v_add_co_u32_e32 v124, vcc, 0x40000, v124
	v_lshl_add_u64 v[118:119], v[118:119], 0, v[154:155]
	v_lshlrev_b32_e32 v154, 1, v123
	v_lshl_add_u64 v[120:121], s[48:49], 0, v[116:117]
	v_lshl_add_u64 v[122:123], s[6:7], 0, v[116:117]
	v_addc_co_u32_e32 v125, vcc, 0, v125, vcc
	v_lshl_add_u64 v[128:129], s[8:9], 0, v[116:117]
	v_lshl_add_u64 v[130:131], v[118:119], 0, v[154:155]
	global_load_dwordx4 v[116:119], v[122:123], off
	s_nop 0
	global_load_dwordx4 v[120:123], v[120:121], off
	s_nop 0
	global_load_dword v154, v[126:127], off
	global_load_dword v139, v[124:125], off
	s_nop 0
	global_load_dwordx4 v[124:127], v[128:129], off
	v_add_u32_e32 v6, s3, v6
	s_waitcnt vmcnt(18)
	v_lshlrev_b32_e32 v34, 16, v9
	v_and_b32_e32 v35, 0xffff0000, v9
	v_lshlrev_b32_e32 v9, 16, v12
	v_and_b32_e32 v21, 0xffff0000, v12
	v_lshlrev_b32_e32 v24, 16, v17
	v_and_b32_e32 v12, 0xffff0000, v17
	v_lshlrev_b32_e32 v17, 16, v14
	v_and_b32_e32 v27, 0xffff0000, v14
	v_max3_f32 v14, v30, v2, v31
	v_lshlrev_b32_e32 v38, 16, v11
	v_lshlrev_b32_e32 v29, 16, v15
	v_and_b32_e32 v39, 0xffff0000, v11
	v_and_b32_e32 v11, 0xffff0000, v15
	v_sub_f32_e32 v15, v30, v14
	v_sub_f32_e32 v2, v2, v14
	v_sub_f32_e32 v14, v31, v14
	v_mul_f32_e32 v15, 0x3fb8aa3b, v15
	v_mul_f32_e32 v2, 0x3fb8aa3b, v2
	v_lshlrev_b32_e32 v32, 16, v8
	v_and_b32_e32 v33, 0xffff0000, v8
	v_lshlrev_b32_e32 v8, 16, v16
	v_and_b32_e32 v20, 0xffff0000, v16
	v_lshlrev_b32_e32 v16, 16, v18
	v_and_b32_e32 v26, 0xffff0000, v18
	v_mul_f32_e32 v14, 0x3fb8aa3b, v14
	v_exp_f32_e32 v15, v15
	v_exp_f32_e32 v18, v2
	v_exp_f32_e32 v14, v14
	v_lshlrev_b32_e32 v36, 16, v10
	v_and_b32_e32 v37, 0xffff0000, v10
	v_add_f32_e32 v2, v15, v18
	v_add_f32_e32 v2, v14, v2
	v_lshlrev_b32_e32 v28, 16, v19
	v_and_b32_e32 v10, 0xffff0000, v19
	v_div_scale_f32 v19, s[14:15], v2, v2, 1.0
	v_rcp_f32_e32 v31, v19
	v_div_scale_f32 v30, vcc, 1.0, v2, 1.0
	v_lshlrev_b32_e32 v25, 16, v13
	v_fma_f32 v40, -v19, v31, 1.0
	v_fmac_f32_e32 v31, v40, v31
	v_mul_f32_e32 v40, v30, v31
	v_fma_f32 v41, -v19, v40, v30
	v_fmac_f32_e32 v40, v41, v31
	v_fma_f32 v19, -v19, v40, v30
	v_div_fmas_f32 v19, v19, v31, v40
	v_div_fixup_f32 v2, v19, v2, 1.0
	v_pk_mul_f32 v[14:15], v[14:15], v[2:3] op_sel_hi:[1,0]
	v_and_b32_e32 v13, 0xffff0000, v13
	v_mul_f32_e32 v30, v18, v2
	v_pk_mul_f32 v[8:9], v[14:15], v[8:9]
	v_pk_mul_f32 v[18:19], v[14:15], v[20:21]
	v_pk_mul_f32 v[20:21], v[14:15], v[24:25]
	v_pk_mul_f32 v[10:11], v[14:15], v[10:11]
	v_pk_mul_f32 v[12:13], v[14:15], v[12:13]
	v_pk_mul_f32 v[16:17], v[14:15], v[16:17]
	v_pk_mul_f32 v[24:25], v[14:15], v[26:27]
	v_pk_mul_f32 v[26:27], v[14:15], v[28:29]
	v_fma_f32 v2, v30, v32, v9
	v_fma_f32 v9, v30, v33, v19
	v_fma_f32 v14, v30, v34, v21
	v_fma_f32 v11, v30, v39, v11
	v_fma_f32 v13, v30, v35, v13
	v_fma_f32 v15, v30, v36, v17
	v_fma_f32 v17, v30, v37, v25
	v_fma_f32 v19, v30, v38, v27
	v_add_f32_e32 v2, v8, v2
	v_add_f32_e32 v8, v18, v9
	v_add_f32_e32 v9, v20, v14
	v_add_f32_e32 v11, v10, v11
	v_add_f32_e32 v12, v12, v13
	v_add_f32_e32 v13, v16, v15
	v_add_f32_e32 v14, v24, v17
	v_add_f32_e32 v15, v26, v19
	v_cvt_pk_bf16_f32 v8, v2, v8
	v_cvt_pk_bf16_f32 v9, v9, v12
	v_cvt_pk_bf16_f32 v10, v13, v14
	v_cvt_pk_bf16_f32 v11, v15, v11
	global_store_dwordx4 v[22:23], v[8:11], off
	s_waitcnt vmcnt(13)
	v_lshlrev_b32_e32 v70, 16, v45
	v_and_b32_e32 v71, 0xffff0000, v45
	v_lshlrev_b32_e32 v45, 16, v48
	v_and_b32_e32 v57, 0xffff0000, v48
	v_lshlrev_b32_e32 v60, 16, v53
	v_and_b32_e32 v48, 0xffff0000, v53
	v_lshlrev_b32_e32 v53, 16, v50
	v_and_b32_e32 v63, 0xffff0000, v50
	v_max3_f32 v50, v66, v150, v67
	v_lshlrev_b32_e32 v74, 16, v47
	v_lshlrev_b32_e32 v65, 16, v51
	v_and_b32_e32 v75, 0xffff0000, v47
	v_and_b32_e32 v47, 0xffff0000, v51
	v_sub_f32_e32 v51, v66, v50
	v_sub_f32_e32 v150, v150, v50
	v_sub_f32_e32 v50, v67, v50
	v_mul_f32_e32 v51, 0x3fb8aa3b, v51
	v_mul_f32_e32 v150, 0x3fb8aa3b, v150
	v_lshlrev_b32_e32 v68, 16, v44
	v_and_b32_e32 v69, 0xffff0000, v44
	v_lshlrev_b32_e32 v44, 16, v52
	v_and_b32_e32 v56, 0xffff0000, v52
	v_lshlrev_b32_e32 v52, 16, v54
	v_and_b32_e32 v62, 0xffff0000, v54
	v_mul_f32_e32 v50, 0x3fb8aa3b, v50
	v_exp_f32_e32 v51, v51
	v_exp_f32_e32 v54, v150
	v_exp_f32_e32 v50, v50
	v_lshlrev_b32_e32 v72, 16, v46
	v_and_b32_e32 v73, 0xffff0000, v46
	v_add_f32_e32 v150, v51, v54
	v_add_f32_e32 v150, v50, v150
	v_lshlrev_b32_e32 v64, 16, v55
	v_and_b32_e32 v46, 0xffff0000, v55
	v_div_scale_f32 v55, s[14:15], v150, v150, 1.0
	v_rcp_f32_e32 v67, v55
	v_div_scale_f32 v66, vcc, 1.0, v150, 1.0
	v_lshlrev_b32_e32 v61, 16, v49
	v_fma_f32 v76, -v55, v67, 1.0
	v_fmac_f32_e32 v67, v76, v67
	v_mul_f32_e32 v76, v66, v67
	v_fma_f32 v77, -v55, v76, v66
	v_fmac_f32_e32 v76, v77, v67
	v_fma_f32 v55, -v55, v76, v66
	v_div_fmas_f32 v55, v55, v67, v76
	v_div_fixup_f32 v150, v55, v150, 1.0
	v_pk_mul_f32 v[50:51], v[50:51], v[150:151] op_sel_hi:[1,0]
	v_and_b32_e32 v49, 0xffff0000, v49
	v_mul_f32_e32 v66, v54, v150
	v_pk_mul_f32 v[44:45], v[50:51], v[44:45]
	v_pk_mul_f32 v[54:55], v[50:51], v[56:57]
	v_pk_mul_f32 v[56:57], v[50:51], v[60:61]
	v_pk_mul_f32 v[46:47], v[50:51], v[46:47]
	v_pk_mul_f32 v[48:49], v[50:51], v[48:49]
	v_pk_mul_f32 v[52:53], v[50:51], v[52:53]
	v_pk_mul_f32 v[60:61], v[50:51], v[62:63]
	v_pk_mul_f32 v[62:63], v[50:51], v[64:65]
	v_fma_f32 v150, v66, v68, v45
	v_fma_f32 v45, v66, v69, v55
	v_fma_f32 v50, v66, v70, v57
	v_fma_f32 v47, v66, v75, v47
	v_fma_f32 v49, v66, v71, v49
	v_fma_f32 v51, v66, v72, v53
	v_fma_f32 v53, v66, v73, v61
	v_fma_f32 v55, v66, v74, v63
	v_add_f32_e32 v150, v44, v150
	v_add_f32_e32 v44, v54, v45
	v_add_f32_e32 v45, v56, v50
	v_add_f32_e32 v47, v46, v47
	v_add_f32_e32 v48, v48, v49
	v_add_f32_e32 v49, v52, v51
	v_add_f32_e32 v50, v60, v53
	v_add_f32_e32 v51, v62, v55
	v_cvt_pk_bf16_f32 v44, v150, v44
	v_cvt_pk_bf16_f32 v45, v45, v48
	v_cvt_pk_bf16_f32 v46, v49, v50
	v_cvt_pk_bf16_f32 v47, v51, v47
	global_store_dwordx4 v[58:59], v[44:47], off
	s_waitcnt vmcnt(8)
	v_lshlrev_b32_e32 v106, 16, v81
	v_and_b32_e32 v107, 0xffff0000, v81
	v_lshlrev_b32_e32 v81, 16, v84
	v_and_b32_e32 v93, 0xffff0000, v84
	v_lshlrev_b32_e32 v96, 16, v89
	v_and_b32_e32 v84, 0xffff0000, v89
	v_lshlrev_b32_e32 v89, 16, v86
	v_and_b32_e32 v99, 0xffff0000, v86
	v_max3_f32 v86, v102, v152, v103
	v_lshlrev_b32_e32 v110, 16, v83
	v_lshlrev_b32_e32 v101, 16, v87
	v_and_b32_e32 v111, 0xffff0000, v83
	v_and_b32_e32 v83, 0xffff0000, v87
	v_sub_f32_e32 v87, v102, v86
	v_sub_f32_e32 v152, v152, v86
	v_sub_f32_e32 v86, v103, v86
	v_mul_f32_e32 v87, 0x3fb8aa3b, v87
	v_mul_f32_e32 v152, 0x3fb8aa3b, v152
	v_lshlrev_b32_e32 v104, 16, v80
	v_and_b32_e32 v105, 0xffff0000, v80
	v_lshlrev_b32_e32 v80, 16, v88
	v_and_b32_e32 v92, 0xffff0000, v88
	v_lshlrev_b32_e32 v88, 16, v90
	v_and_b32_e32 v98, 0xffff0000, v90
	v_mul_f32_e32 v86, 0x3fb8aa3b, v86
	v_exp_f32_e32 v87, v87
	v_exp_f32_e32 v90, v152
	v_exp_f32_e32 v86, v86
	v_lshlrev_b32_e32 v108, 16, v82
	v_and_b32_e32 v109, 0xffff0000, v82
	v_add_f32_e32 v152, v87, v90
	v_add_f32_e32 v152, v86, v152
	v_lshlrev_b32_e32 v100, 16, v91
	v_and_b32_e32 v82, 0xffff0000, v91
	v_div_scale_f32 v91, s[14:15], v152, v152, 1.0
	v_rcp_f32_e32 v103, v91
	v_div_scale_f32 v102, vcc, 1.0, v152, 1.0
	v_lshlrev_b32_e32 v97, 16, v85
	v_fma_f32 v112, -v91, v103, 1.0
	v_fmac_f32_e32 v103, v112, v103
	v_mul_f32_e32 v112, v102, v103
	v_fma_f32 v113, -v91, v112, v102
	v_fmac_f32_e32 v112, v113, v103
	v_fma_f32 v91, -v91, v112, v102
	v_div_fmas_f32 v91, v91, v103, v112
	v_div_fixup_f32 v152, v91, v152, 1.0
	v_pk_mul_f32 v[86:87], v[86:87], v[152:153] op_sel_hi:[1,0]
	v_and_b32_e32 v85, 0xffff0000, v85
	v_mul_f32_e32 v102, v90, v152
	v_pk_mul_f32 v[80:81], v[86:87], v[80:81]
	v_pk_mul_f32 v[90:91], v[86:87], v[92:93]
	v_pk_mul_f32 v[92:93], v[86:87], v[96:97]
	v_pk_mul_f32 v[82:83], v[86:87], v[82:83]
	v_pk_mul_f32 v[84:85], v[86:87], v[84:85]
	v_pk_mul_f32 v[88:89], v[86:87], v[88:89]
	v_pk_mul_f32 v[96:97], v[86:87], v[98:99]
	v_pk_mul_f32 v[98:99], v[86:87], v[100:101]
	v_fma_f32 v152, v102, v104, v81
	v_fma_f32 v81, v102, v105, v91
	v_fma_f32 v86, v102, v106, v93
	v_fma_f32 v83, v102, v111, v83
	v_fma_f32 v85, v102, v107, v85
	v_fma_f32 v87, v102, v108, v89
	v_fma_f32 v89, v102, v109, v97
	v_fma_f32 v91, v102, v110, v99
	v_add_f32_e32 v152, v80, v152
	v_add_f32_e32 v80, v90, v81
	v_add_f32_e32 v81, v92, v86
	v_add_f32_e32 v83, v82, v83
	v_add_f32_e32 v84, v84, v85
	v_add_f32_e32 v85, v88, v87
	v_add_f32_e32 v86, v96, v89
	v_add_f32_e32 v87, v98, v91
	v_cvt_pk_bf16_f32 v80, v152, v80
	v_cvt_pk_bf16_f32 v81, v81, v84
	v_cvt_pk_bf16_f32 v82, v85, v86
	v_cvt_pk_bf16_f32 v83, v87, v83
	global_store_dwordx4 v[94:95], v[80:83], off
	s_waitcnt vmcnt(3)
	v_lshlrev_b32_e32 v142, 16, v117
	v_and_b32_e32 v143, 0xffff0000, v117
	v_lshlrev_b32_e32 v117, 16, v120
	v_and_b32_e32 v129, 0xffff0000, v120
	v_lshlrev_b32_e32 v132, 16, v125
	v_and_b32_e32 v120, 0xffff0000, v125
	v_lshlrev_b32_e32 v125, 16, v122
	v_and_b32_e32 v135, 0xffff0000, v122
	v_max3_f32 v122, v138, v154, v139
	v_lshlrev_b32_e32 v146, 16, v119
	v_lshlrev_b32_e32 v137, 16, v123
	v_and_b32_e32 v147, 0xffff0000, v119
	v_and_b32_e32 v119, 0xffff0000, v123
	v_sub_f32_e32 v123, v138, v122
	v_sub_f32_e32 v154, v154, v122
	v_sub_f32_e32 v122, v139, v122
	v_mul_f32_e32 v123, 0x3fb8aa3b, v123
	v_mul_f32_e32 v154, 0x3fb8aa3b, v154
	v_lshlrev_b32_e32 v140, 16, v116
	v_and_b32_e32 v141, 0xffff0000, v116
	v_lshlrev_b32_e32 v116, 16, v124
	v_and_b32_e32 v128, 0xffff0000, v124
	v_lshlrev_b32_e32 v124, 16, v126
	v_and_b32_e32 v134, 0xffff0000, v126
	v_mul_f32_e32 v122, 0x3fb8aa3b, v122
	v_exp_f32_e32 v123, v123
	v_exp_f32_e32 v126, v154
	v_exp_f32_e32 v122, v122
	v_lshlrev_b32_e32 v144, 16, v118
	v_and_b32_e32 v145, 0xffff0000, v118
	v_add_f32_e32 v154, v123, v126
	v_add_f32_e32 v154, v122, v154
	v_lshlrev_b32_e32 v136, 16, v127
	v_and_b32_e32 v118, 0xffff0000, v127
	v_div_scale_f32 v127, s[14:15], v154, v154, 1.0
	v_rcp_f32_e32 v139, v127
	v_div_scale_f32 v138, vcc, 1.0, v154, 1.0
	v_lshlrev_b32_e32 v133, 16, v121
	v_fma_f32 v148, -v127, v139, 1.0
	v_fmac_f32_e32 v139, v148, v139
	v_mul_f32_e32 v148, v138, v139
	v_fma_f32 v149, -v127, v148, v138
	v_fmac_f32_e32 v148, v149, v139
	v_fma_f32 v127, -v127, v148, v138
	v_div_fmas_f32 v127, v127, v139, v148
	v_div_fixup_f32 v154, v127, v154, 1.0
	v_pk_mul_f32 v[122:123], v[122:123], v[154:155] op_sel_hi:[1,0]
	v_and_b32_e32 v121, 0xffff0000, v121
	v_mul_f32_e32 v138, v126, v154
	v_pk_mul_f32 v[116:117], v[122:123], v[116:117]
	v_pk_mul_f32 v[126:127], v[122:123], v[128:129]
	v_pk_mul_f32 v[128:129], v[122:123], v[132:133]
	v_pk_mul_f32 v[118:119], v[122:123], v[118:119]
	v_pk_mul_f32 v[120:121], v[122:123], v[120:121]
	v_pk_mul_f32 v[124:125], v[122:123], v[124:125]
	v_pk_mul_f32 v[132:133], v[122:123], v[134:135]
	v_pk_mul_f32 v[134:135], v[122:123], v[136:137]
	v_fma_f32 v154, v138, v140, v117
	v_fma_f32 v117, v138, v141, v127
	v_fma_f32 v122, v138, v142, v129
	v_fma_f32 v119, v138, v147, v119
	v_fma_f32 v121, v138, v143, v121
	v_fma_f32 v123, v138, v144, v125
	v_fma_f32 v125, v138, v145, v133
	v_fma_f32 v127, v138, v146, v135
	v_add_f32_e32 v154, v116, v154
	v_add_f32_e32 v116, v126, v117
	v_add_f32_e32 v117, v128, v122
	v_add_f32_e32 v119, v118, v119
	v_add_f32_e32 v120, v120, v121
	v_add_f32_e32 v121, v124, v123
	v_add_f32_e32 v122, v132, v125
	v_add_f32_e32 v123, v134, v127
	v_cvt_pk_bf16_f32 v116, v154, v116
	v_cvt_pk_bf16_f32 v117, v117, v120
	v_cvt_pk_bf16_f32 v118, v121, v122
	v_cvt_pk_bf16_f32 v119, v123, v119
	global_store_dwordx4 v[130:131], v[116:119], off
	s_branch .LBB0_613
